# GDN scan: output stores as global stores and no vmcnt(0) at the per-chunk barrier for the compute waves (stagers keep their own DMA wait)
# baseline (speedup 1.0000x reference)
.LBB0_522:
	s_add_i32 s87, s87, 1
	s_add_i32 s35, s35, 4
	v_mov_b64_e32 v[36:37], v[68:69]
	v_mov_b64_e32 v[40:41], v[64:65]
	v_mov_b64_e32 v[44:45], v[72:73]
	v_mov_b64_e32 v[48:49], v[76:77]
	v_add_u32_e32 v116, 64, v116
	s_cmp_lg_u32 s87, 64
	v_mov_b64_e32 v[38:39], v[70:71]
	v_mov_b64_e32 v[42:43], v[66:67]
	v_mov_b64_e32 v[46:47], v[74:75]
	v_mov_b64_e32 v[50:51], v[78:79]
	v_mov_b32_e32 v52, v80
	v_mov_b32_e32 v53, v81
	v_mov_b32_e32 v54, v82
	v_mov_b32_e32 v55, v83
	v_mov_b32_e32 v56, v60
	v_mov_b32_e32 v57, v61
	v_mov_b32_e32 v58, v62
	v_mov_b32_e32 v59, v63
	s_waitcnt lgkmcnt(0)
	s_barrier
	s_cbranch_scc0 .LBB0_566

.LBB0_551:
	v_mov_b64_e32 v[48:49], v[76:77]
	v_mov_b64_e32 v[40:41], v[72:73]
	v_mov_b64_e32 v[36:37], v[64:65]
	v_mov_b64_e32 v[44:45], v[68:69]
	s_andn2_b64 vcc, exec, s[60:61]
	v_mov_b64_e32 v[50:51], v[78:79]
	v_mov_b64_e32 v[42:43], v[74:75]
	v_mov_b64_e32 v[38:39], v[66:67]
	v_mov_b64_e32 v[46:47], v[70:71]
	s_cbranch_vccnz .LBB0_553
	v_add_u32_e32 v16, 0x20800, v118
	ds_read_b128 v[36:39], v16
	ds_read_b128 v[48:51], v16 offset:1024
	v_add_u32_e32 v16, s88, v125
	v_add_u32_e32 v16, 0xd000, v16
	ds_read_b64 v[40:41], v16 offset:0
	ds_read_b64 v[42:43], v16 offset:32
	ds_read_b64 v[44:45], v16 offset:0x900
	ds_read_b64 v[46:47], v16 offset:0x920
	ds_read_b64 v[52:53], v16 offset:0x1200
	ds_read_b64 v[54:55], v16 offset:0x1220
	ds_read_b64 v[56:57], v16 offset:0x1b00
	ds_read_b64 v[58:59], v16 offset:0x1b20
	ds_read_b64 v[128:129], v16 offset:64
	ds_read_b64 v[130:131], v16 offset:0x60
	ds_read_b64 v[132:133], v16 offset:0x940
	ds_read_b64 v[134:135], v16 offset:0x960
	ds_read_b64 v[136:137], v16 offset:0x1240
	ds_read_b64 v[138:139], v16 offset:0x1260
	ds_read_b64 v[140:141], v16 offset:0x1b40
	ds_read_b64 v[142:143], v16 offset:0x1b60
	v_ashrrev_i32_e32 v117, 31, v116
	s_waitcnt lgkmcnt(0)
	s_waitcnt lgkmcnt(0)
	v_lshlrev_b64 v[18:19], 11, v[116:117]
	s_waitcnt lgkmcnt(0)
	v_mfma_f32_16x16x32_bf16 v[40:43], v[40:43], v[36:39], v[64:67]
	v_lshl_add_u64 v[18:19], v[92:93], 0, v[18:19]
	s_mov_b32 s52, 0x9000
	v_mfma_f32_16x16x32_bf16 v[44:47], v[44:47], v[36:39], v[68:71]
	v_mfma_f32_16x16x32_bf16 v[52:55], v[52:55], v[36:39], v[72:75]
	v_mfma_f32_16x16x32_bf16 v[56:59], v[56:59], v[36:39], v[76:79]
	v_mfma_f32_16x16x32_bf16 v[36:39], v[128:131], v[48:51], v[40:43]
	s_nop 7
	global_store_dword v[18:19], v36, off
	global_store_dword v[18:19], v37, off offset:2048
	v_mfma_f32_16x16x32_bf16 v[44:47], v[132:135], v[48:51], v[44:47]
	v_mfma_f32_16x16x32_bf16 v[40:43], v[136:139], v[48:51], v[52:55]
	s_nop 2
	v_add_co_u32_e32 v52, vcc, s68, v18
	v_mfma_f32_16x16x32_bf16 v[48:51], v[140:143], v[48:51], v[56:59]
	s_nop 0
	v_addc_co_u32_e32 v53, vcc, 0, v19, vcc
	global_store_dword v[52:53], v38, off
	global_store_dword v[52:53], v39, off offset:2048
	v_add_co_u32_e32 v52, vcc, s47, v18
	s_nop 1
	v_addc_co_u32_e32 v53, vcc, 0, v19, vcc
	global_store_dword v[52:53], v44, off
	global_store_dword v[52:53], v45, off offset:2048
	v_add_co_u32_e32 v52, vcc, s52, v18
	s_mov_b32 s52, 0x10000
	s_nop 0
	v_addc_co_u32_e32 v53, vcc, 0, v19, vcc
	global_store_dword v[52:53], v46, off
	global_store_dword v[52:53], v47, off offset:2048
	v_add_co_u32_e32 v52, vcc, s52, v18
	s_nop 1
	v_addc_co_u32_e32 v53, vcc, 0, v19, vcc
	global_store_dword v[52:53], v40, off
	global_store_dword v[52:53], v41, off offset:2048
	v_add_co_u32_e32 v52, vcc, 0x11000, v18
	s_nop 1
	v_addc_co_u32_e32 v53, vcc, 0, v19, vcc
	global_store_dword v[52:53], v42, off
	global_store_dword v[52:53], v43, off offset:2048
	v_add_co_u32_e32 v52, vcc, 0x18000, v18
	s_nop 1
	v_addc_co_u32_e32 v53, vcc, 0, v19, vcc
	v_add_co_u32_e32 v18, vcc, 0x19000, v18
	global_store_dword v[52:53], v48, off
	global_store_dword v[52:53], v49, off offset:2048
	v_addc_co_u32_e32 v19, vcc, 0, v19, vcc
	global_store_dword v[18:19], v50, off
	global_store_dword v[18:19], v51, off offset:2048
